# diff L0 loop: full softmax migration (exps, sums, packs in the PV section; score section is MFMA only) on top of early-exp
# baseline (speedup 1.0000x reference)
.LBB0_904:
	v_add_f32_e32 v1, v1, v116
	s_add_u32 s0, s18, 0x240000
	v_add_f32_e32 v1, 0, v1
	v_add_f32_e32 v66, v66, v67
	s_addc_u32 s1, s19, 0
	v_add_f32_e32 v1, v1, v66
	v_lshl_add_u64 v[66:67], v[72:73], 1, s[0:1]
	s_mov_b32 m0, s35
	v_exp_f32_e32 v175, v106
	global_load_lds_dwordx4 v[66:67], off
	v_lshl_add_u64 v[66:67], v[70:71], 1, s[0:1]
	s_mov_b32 m0, s86
	v_exp_f32_e32 v176, v107
	global_load_lds_dwordx4 v[66:67], off
	v_exp_f32_e32 v177, v108
	v_exp_f32_e32 v178, v109
	v_exp_f32_e32 v179, v110
	v_exp_f32_e32 v180, v111
	v_exp_f32_e32 v181, v112
	v_exp_f32_e32 v192, v113
	ds_read_b128 v[66:69], v188 offset:40960
	ds_read_b128 v[70:73], v188 offset:45056
	ds_read_b128 v[106:109], v189 offset:40960
	ds_read_b128 v[110:113], v189 offset:45056
	ds_read_b128 v[116:119], v190 offset:40960
	ds_read_b128 v[120:123], v190 offset:45056
	ds_read_b128 v[124:127], v191 offset:40960
	ds_read_b128 v[170:173], v191 offset:45056
	v_exp_f32_e32 v151, v98
	v_exp_f32_e32 v153, v99
	v_exp_f32_e32 v155, v100
	v_exp_f32_e32 v157, v101
	v_exp_f32_e32 v159, v102
	v_exp_f32_e32 v161, v103
	v_exp_f32_e32 v163, v104
	v_exp_f32_e32 v174, v105
	s_waitcnt lgkmcnt(0)
	v_mfma_f32_32x32x16_bf16 v[90:105], v[66:69], v[128:131], 0
	v_exp_f32_e32 v193, v74
	v_exp_f32_e32 v194, v75
	v_exp_f32_e32 v195, v76
	v_exp_f32_e32 v196, v77
	v_exp_f32_e32 v197, v78
	v_exp_f32_e32 v198, v79
	v_exp_f32_e32 v199, v80
	v_exp_f32_e32 v200, v81
	v_mfma_f32_32x32x16_bf16 v[66:81], v[70:73], v[128:131], 0
	v_mfma_f32_32x32x16_bf16 v[90:105], v[106:109], v[132:135], v[90:105]
	v_exp_f32_e32 v82, v82
	v_exp_f32_e32 v83, v83
	v_exp_f32_e32 v84, v84
	v_exp_f32_e32 v85, v85
	v_exp_f32_e32 v86, v86
	v_exp_f32_e32 v87, v87
	v_exp_f32_e32 v88, v88
	v_mfma_f32_32x32x16_bf16 v[66:81], v[110:113], v[132:135], v[66:81]
	v_exp_f32_e32 v89, v89
	v_add_f32_e32 v106, v151, v153
	v_add_f32_e32 v107, v193, v194
	v_mfma_f32_32x32x16_bf16 v[90:105], v[116:119], v[136:139], v[90:105]
	v_add_f32_e32 v106, v106, v155
	v_add_f32_e32 v107, v107, v195
	v_cvt_pk_bf16_f32 v108, v159, v161
	v_add_f32_e32 v106, v106, v157
	v_add_f32_e32 v107, v107, v196
	v_cvt_pk_bf16_f32 v109, v163, v174
	v_add_f32_e32 v106, v106, v159
	v_add_f32_e32 v107, v107, v197
	v_mfma_f32_32x32x16_bf16 v[66:81], v[120:123], v[136:139], v[66:81]
	v_add_f32_e32 v106, v106, v161
	v_add_f32_e32 v107, v107, v198
	s_nop 0
	v_add_f32_e32 v106, v106, v163
	v_add_f32_e32 v107, v107, v199
	s_nop 0
	v_add_f32_e32 v106, v106, v174
	v_add_f32_e32 v107, v107, v200
	s_nop 0
	v_add_f32_e32 v106, v106, v175
	v_add_f32_e32 v107, v107, v82
	s_nop 0
	v_add_f32_e32 v106, v106, v176
	v_add_f32_e32 v107, v107, v83
	s_nop 0
	v_add_f32_e32 v106, v106, v177
	v_add_f32_e32 v107, v107, v84
	s_nop 0
	v_add_f32_e32 v106, v106, v178
	v_add_f32_e32 v107, v107, v85
	s_nop 0
	v_add_f32_e32 v106, v106, v179
	v_add_f32_e32 v107, v107, v86
	s_nop 0
	v_add_f32_e32 v106, v106, v180
	v_add_f32_e32 v107, v107, v87
	s_nop 0
	v_add_f32_e32 v106, v106, v181
	v_add_f32_e32 v107, v107, v88
	s_nop 0
	v_add_f32_e32 v106, v106, v192
	v_add_f32_e32 v107, v107, v89
	s_nop 0
	v_add_f32_e32 v106, v106, v107
	v_mov_b32_e32 v107, v106
	s_nop 1
	v_permlane32_swap_b32_e32 v106, v107
	v_add_f32_e32 v106, v106, v107
	v_add_f32_e32 v149, v1, v106
	v_cvt_pk_bf16_f32 v106, v151, v153
	v_cvt_pk_bf16_f32 v107, v155, v157
	s_nop 0
	v_permlane32_swap_b32_e32 v106, v108
	v_permlane32_swap_b32_e32 v107, v109
	v_mfma_f32_32x32x16_bf16 v[90:105], v[124:127], v[140:143], v[90:105]
	v_cvt_pk_bf16_f32 v110, v175, v176
	v_cvt_pk_bf16_f32 v111, v177, v178
	v_cvt_pk_bf16_f32 v112, v179, v180
	v_cvt_pk_bf16_f32 v113, v181, v192
	v_cvt_pk_bf16_f32 v116, v193, v194
	v_cvt_pk_bf16_f32 v117, v195, v196
	v_cvt_pk_bf16_f32 v118, v197, v198
	v_mfma_f32_32x32x16_bf16 v[66:81], v[170:173], v[140:143], v[66:81]
	v_cvt_pk_bf16_f32 v119, v199, v200
	v_cvt_pk_bf16_f32 v120, v82, v83
	v_cvt_pk_bf16_f32 v121, v84, v85
	v_cvt_pk_bf16_f32 v122, v86, v87
	v_cvt_pk_bf16_f32 v123, v88, v89
	v_permlane32_swap_b32_e32 v110, v112
	v_permlane32_swap_b32_e32 v111, v113
	v_permlane32_swap_b32_e32 v116, v118
	v_permlane32_swap_b32_e32 v117, v119
	v_permlane32_swap_b32_e32 v120, v122
	v_permlane32_swap_b32_e32 v121, v123
	ds_read_b64_tr_b16 v[82:83], v184 offset:0
	ds_read_b64_tr_b16 v[84:85], v184 offset:0x800
	ds_read_b64_tr_b16 v[86:87], v184 offset:0x1000
	ds_read_b64_tr_b16 v[88:89], v184 offset:0x1800
	ds_read_b64_tr_b16 v[124:125], v184 offset:0x2000
	ds_read_b64_tr_b16 v[126:127], v184 offset:0x2800
	ds_read_b64_tr_b16 v[170:171], v184 offset:0x3000
	ds_read_b64_tr_b16 v[172:173], v184 offset:0x3800
	ds_read_b64_tr_b16 v[174:175], v184 offset:0x200
	ds_read_b64_tr_b16 v[176:177], v184 offset:0xa00
	ds_read_b64_tr_b16 v[178:179], v184 offset:0x1200
	ds_read_b64_tr_b16 v[180:181], v184 offset:0x1a00
	ds_read_b64_tr_b16 v[192:193], v184 offset:0x2200
	ds_read_b64_tr_b16 v[194:195], v184 offset:0x2a00
	ds_read_b64_tr_b16 v[196:197], v184 offset:0x3200
	ds_read_b64_tr_b16 v[198:199], v184 offset:0x3a00
	s_waitcnt lgkmcnt(8)
	s_nop 0
	v_mfma_f32_32x32x16_bf16 v[2:17], v[106:109], v[82:85], v[2:17]
	v_exp_f32_e32 v1, v91
	v_exp_f32_e32 v82, v92
	v_exp_f32_e32 v83, v93
	v_mfma_f32_32x32x16_bf16 v[2:17], v[110:113], v[86:89], v[2:17]
	v_exp_f32_e32 v88, v90
	v_mfma_f32_32x32x16_bf16 v[2:17], v[116:119], v[124:127], v[2:17]
	v_mfma_f32_32x32x16_bf16 v[2:17], v[120:123], v[170:173], v[2:17]
	ds_read_b64_tr_b16 v[90:91], v184 offset:0x400
	ds_read_b64_tr_b16 v[92:93], v184 offset:0xc00
	ds_read_b64_tr_b16 v[124:125], v184 offset:0x1400
	ds_read_b64_tr_b16 v[126:127], v184 offset:0x1c00
	ds_read_b64_tr_b16 v[170:171], v184 offset:0x2400
	ds_read_b64_tr_b16 v[172:173], v184 offset:0x2c00
	ds_read_b64_tr_b16 v[200:201], v184 offset:0x3400
	ds_read_b64_tr_b16 v[202:203], v184 offset:0x3c00
	s_waitcnt lgkmcnt(8)
	v_mfma_f32_32x32x16_bf16 v[18:33], v[106:109], v[174:177], v[18:33]
	v_exp_f32_e32 v84, v94
	v_exp_f32_e32 v85, v95
	v_exp_f32_e32 v86, v96
	v_exp_f32_e32 v87, v97
	v_mfma_f32_32x32x16_bf16 v[18:33], v[110:113], v[178:181], v[18:33]
	v_mfma_f32_32x32x16_bf16 v[18:33], v[116:119], v[192:195], v[18:33]
	v_mfma_f32_32x32x16_bf16 v[18:33], v[120:123], v[196:199], v[18:33]
	ds_read_b64_tr_b16 v[94:95], v184 offset:0x600
	ds_read_b64_tr_b16 v[96:97], v184 offset:0xe00
	ds_read_b64_tr_b16 v[174:175], v184 offset:0x1600
	ds_read_b64_tr_b16 v[176:177], v184 offset:0x1e00
	ds_read_b64_tr_b16 v[178:179], v184 offset:0x2600
	ds_read_b64_tr_b16 v[180:181], v184 offset:0x2e00
	ds_read_b64_tr_b16 v[192:193], v184 offset:0x3600
	ds_read_b64_tr_b16 v[194:195], v184 offset:0x3e00
	s_waitcnt lgkmcnt(8)
	v_mfma_f32_32x32x16_bf16 v[34:49], v[106:109], v[90:93], v[34:49]
	v_exp_f32_e32 v90, v98
	v_exp_f32_e32 v89, v99
	v_exp_f32_e32 v92, v100
	v_exp_f32_e32 v91, v101
	v_mfma_f32_32x32x16_bf16 v[34:49], v[110:113], v[124:127], v[34:49]
	v_mfma_f32_32x32x16_bf16 v[34:49], v[116:119], v[170:173], v[34:49]
	v_mfma_f32_32x32x16_bf16 v[34:49], v[120:123], v[200:203], v[34:49]
	s_waitcnt lgkmcnt(0)
	v_mfma_f32_32x32x16_bf16 v[50:65], v[106:109], v[94:97], v[50:65]
	v_exp_f32_e32 v94, v102
	v_exp_f32_e32 v93, v103
	v_exp_f32_e32 v95, v104
	v_exp_f32_e32 v151, v105
	v_mfma_f32_32x32x16_bf16 v[50:65], v[110:113], v[174:177], v[50:65]
	v_mfma_f32_32x32x16_bf16 v[50:65], v[116:119], v[178:181], v[50:65]
	v_mfma_f32_32x32x16_bf16 v[50:65], v[120:123], v[192:195], v[50:65]
	s_waitcnt vmcnt(0)
	s_and_b64 vcc, exec, s[4:5]
	s_waitcnt vmcnt(0)
	s_barrier
	s_cbranch_vccnz .LBB0_911
	v_readlane_b32 s36, v243, 63
	v_readlane_b32 s50, v242, 13
	v_readlane_b32 s51, v242, 14
	s_add_u32 s4, s50, s88
	v_mov_b32_e32 v96, s25
	v_mov_b32_e32 v97, v145
	s_addc_u32 s5, s51, s87
	s_add_i32 s92, s92, s91
	v_lshl_add_u64 v[170:171], v[114:115], 1, v[96:97]
	v_add_u32_e32 v96, s92, v182
	v_add_u32_e32 v97, s10, v166
	v_mul_lo_u32 v96, v96, s22
	v_and_b32_e32 v98, 0x60, v97
	v_or3_b32 v96, v169, v96, v98
	v_ashrrev_i32_e32 v97, 31, v96
	s_add_i32 s90, s90, s89
	v_lshlrev_b64 v[172:173], 1, v[96:97]
	v_add_u32_e32 v96, s90, v182
	v_mul_lo_u32 v96, v96, s22
	v_or3_b32 v96, v169, v96, v98
	v_ashrrev_i32_e32 v97, 31, v96
	v_lshlrev_b64 v[174:175], 1, v[96:97]
	v_or_b32_e32 v172, s24, v172
	v_or_b32_e32 v174, s24, v174
	s_mov_b32 s16, 6
	v_readlane_b32 s37, v242, 0
	v_readlane_b32 s38, v242, 1
	v_readlane_b32 s39, v242, 2
	v_readlane_b32 s40, v242, 3
	v_readlane_b32 s41, v242, 4
	v_readlane_b32 s42, v242, 5
	v_readlane_b32 s43, v242, 6
	v_readlane_b32 s44, v242, 7
	v_readlane_b32 s45, v242, 8
	v_readlane_b32 s46, v242, 9
	v_readlane_b32 s47, v242, 10
	v_readlane_b32 s48, v242, 11
	v_readlane_b32 s49, v242, 12
	v_exp_f32_e32 v66, v66
	v_exp_f32_e32 v67, v67
	v_exp_f32_e32 v68, v68
	v_exp_f32_e32 v69, v69
	v_exp_f32_e32 v70, v70
	v_exp_f32_e32 v71, v71
	v_exp_f32_e32 v72, v72
	v_exp_f32_e32 v73, v73
	v_exp_f32_e32 v74, v74
	v_exp_f32_e32 v75, v75
	v_exp_f32_e32 v76, v76
	v_exp_f32_e32 v77, v77
	v_exp_f32_e32 v78, v78
	v_exp_f32_e32 v79, v79
	v_exp_f32_e32 v80, v80
	v_exp_f32_e32 v81, v81
	v_add_f32_e32 v96, v88, v1
	v_add_f32_e32 v97, v66, v67
	v_add_f32_e32 v96, v96, v82
	v_add_f32_e32 v97, v97, v68
	v_add_f32_e32 v96, v96, v83
	v_add_f32_e32 v97, v97, v69
	v_add_f32_e32 v96, v96, v84
	v_add_f32_e32 v97, v97, v70
	v_add_f32_e32 v96, v96, v85
	v_add_f32_e32 v97, v97, v71
	v_add_f32_e32 v96, v96, v86
	v_add_f32_e32 v97, v97, v72
	v_add_f32_e32 v96, v96, v87
	v_add_f32_e32 v97, v97, v73
	v_add_f32_e32 v96, v96, v90
	v_add_f32_e32 v97, v97, v74
	v_add_f32_e32 v96, v96, v89
	v_add_f32_e32 v97, v97, v75
	v_add_f32_e32 v96, v96, v92
	v_add_f32_e32 v97, v97, v76
	v_add_f32_e32 v96, v96, v91
	v_add_f32_e32 v97, v97, v77
	v_add_f32_e32 v96, v96, v94
	v_add_f32_e32 v97, v97, v78
	v_add_f32_e32 v96, v96, v93
	v_add_f32_e32 v97, v97, v79
	v_add_f32_e32 v96, v96, v95
	v_add_f32_e32 v97, v97, v80
	v_add_f32_e32 v96, v96, v151
	v_add_f32_e32 v97, v97, v81
	v_add_f32_e32 v96, v96, v97
	v_mov_b32_e32 v98, v96
	v_cvt_pk_bf16_f32 v222, v88, v1
	v_cvt_pk_bf16_f32 v223, v82, v83
	v_cvt_pk_bf16_f32 v224, v84, v85
	v_cvt_pk_bf16_f32 v225, v86, v87
	v_cvt_pk_bf16_f32 v226, v90, v89
	v_cvt_pk_bf16_f32 v227, v92, v91
	v_cvt_pk_bf16_f32 v228, v94, v93
	v_cvt_pk_bf16_f32 v229, v95, v151
	v_cvt_pk_bf16_f32 v230, v66, v67
	v_cvt_pk_bf16_f32 v231, v68, v69
	v_cvt_pk_bf16_f32 v232, v70, v71
	v_cvt_pk_bf16_f32 v233, v72, v73
	v_cvt_pk_bf16_f32 v234, v74, v75
	v_cvt_pk_bf16_f32 v235, v76, v77
	v_cvt_pk_bf16_f32 v236, v78, v79
	v_cvt_pk_bf16_f32 v237, v80, v81
	v_permlane32_swap_b32_e32 v96, v98
	v_add_f32_e32 v96, v96, v98
	v_add_f32_e32 v149, v149, v96
	v_permlane32_swap_b32_e32 v222, v224
	v_permlane32_swap_b32_e32 v223, v225
	v_permlane32_swap_b32_e32 v226, v228
	v_permlane32_swap_b32_e32 v227, v229
	v_permlane32_swap_b32_e32 v230, v232
	v_permlane32_swap_b32_e32 v231, v233
	v_permlane32_swap_b32_e32 v234, v236
	v_permlane32_swap_b32_e32 v235, v237
	s_branch .LBB0_907
.LBB0_906:
	s_mov_b32 m0, s35
	v_lshl_add_u64 v[66:67], v[178:179], 0, s[12:13]
	global_load_lds_dwordx4 v[66:67], off
	s_mov_b32 m0, s86
	v_lshl_add_u64 v[66:67], v[176:177], 0, s[12:13]
	global_load_lds_dwordx4 v[66:67], off
	ds_read_b128 v[66:69], v188 offset:40960
	ds_read_b128 v[70:73], v188 offset:45056
	ds_read_b128 v[82:85], v189 offset:40960
	ds_read_b128 v[86:89], v189 offset:45056
	ds_read_b128 v[90:93], v190 offset:40960
	ds_read_b128 v[176:179], v190 offset:45056
	ds_read_b128 v[192:195], v191 offset:40960
	ds_read_b128 v[196:199], v191 offset:45056
	s_waitcnt lgkmcnt(0)
	v_mfma_f32_32x32x16_bf16 v[112:127], v[66:69], v[128:131], 0
	v_mfma_f32_32x32x16_bf16 v[66:81], v[70:73], v[128:131], 0
	v_mfma_f32_32x32x16_bf16 v[66:81], v[86:89], v[132:135], v[66:81]
	v_mfma_f32_32x32x16_bf16 v[112:127], v[82:85], v[132:135], v[112:127]
	v_mfma_f32_32x32x16_bf16 v[66:81], v[176:179], v[136:139], v[66:81]
	v_mfma_f32_32x32x16_bf16 v[112:127], v[90:93], v[136:139], v[112:127]
	v_mfma_f32_32x32x16_bf16 v[66:81], v[196:199], v[140:143], v[66:81]
	v_mfma_f32_32x32x16_bf16 v[112:127], v[192:195], v[140:143], v[112:127]
	ds_read_b64_tr_b16 v[82:83], v184 offset:0
	ds_read_b64_tr_b16 v[84:85], v184 offset:0x800
	ds_read_b64_tr_b16 v[86:87], v184 offset:0x1000
	ds_read_b64_tr_b16 v[88:89], v184 offset:0x1800
	ds_read_b64_tr_b16 v[90:91], v184 offset:0x2000
	ds_read_b64_tr_b16 v[92:93], v184 offset:0x2800
	ds_read_b64_tr_b16 v[176:177], v184 offset:0x3000
	ds_read_b64_tr_b16 v[178:179], v184 offset:0x3800
	ds_read_b64_tr_b16 v[192:193], v184 offset:0x200
	ds_read_b64_tr_b16 v[194:195], v184 offset:0xa00
	ds_read_b64_tr_b16 v[196:197], v184 offset:0x1200
	ds_read_b64_tr_b16 v[198:199], v184 offset:0x1a00
	ds_read_b64_tr_b16 v[200:201], v184 offset:0x2200
	ds_read_b64_tr_b16 v[202:203], v184 offset:0x2a00
	ds_read_b64_tr_b16 v[204:205], v184 offset:0x3200
	ds_read_b64_tr_b16 v[206:207], v184 offset:0x3a00
	s_waitcnt lgkmcnt(8)
	v_mfma_f32_32x32x16_bf16 v[2:17], v[238:241], v[82:85], v[2:17]
	v_exp_f32_e32 v112, v112
	v_exp_f32_e32 v113, v113
	v_exp_f32_e32 v114, v114
	v_exp_f32_e32 v115, v115
	v_exp_f32_e32 v116, v116
	v_exp_f32_e32 v117, v117
	v_mfma_f32_32x32x16_bf16 v[2:17], v[244:247], v[86:89], v[2:17]
	v_exp_f32_e32 v118, v118
	v_exp_f32_e32 v119, v119
	v_exp_f32_e32 v120, v120
	v_exp_f32_e32 v121, v121
	v_exp_f32_e32 v122, v122
	v_exp_f32_e32 v123, v123
	v_mfma_f32_32x32x16_bf16 v[2:17], v[248:251], v[90:93], v[2:17]
	v_exp_f32_e32 v124, v124
	v_exp_f32_e32 v125, v125
	v_exp_f32_e32 v126, v126
	v_exp_f32_e32 v127, v127
	v_exp_f32_e32 v66, v66
	v_exp_f32_e32 v67, v67
	v_mfma_f32_32x32x16_bf16 v[2:17], v[252:255], v[176:179], v[2:17]
	v_exp_f32_e32 v68, v68
	v_exp_f32_e32 v69, v69
	v_exp_f32_e32 v70, v70
	v_exp_f32_e32 v71, v71
	v_exp_f32_e32 v72, v72
	v_exp_f32_e32 v73, v73
	ds_read_b64_tr_b16 v[82:83], v184 offset:0x400
	ds_read_b64_tr_b16 v[84:85], v184 offset:0xc00
	ds_read_b64_tr_b16 v[86:87], v184 offset:0x1400
	ds_read_b64_tr_b16 v[88:89], v184 offset:0x1c00
	ds_read_b64_tr_b16 v[90:91], v184 offset:0x2400
	ds_read_b64_tr_b16 v[92:93], v184 offset:0x2c00
	ds_read_b64_tr_b16 v[176:177], v184 offset:0x3400
	ds_read_b64_tr_b16 v[178:179], v184 offset:0x3c00
	s_waitcnt lgkmcnt(8)
	v_mfma_f32_32x32x16_bf16 v[18:33], v[238:241], v[192:195], v[18:33]
	v_exp_f32_e32 v74, v74
	v_exp_f32_e32 v75, v75
	v_exp_f32_e32 v76, v76
	v_exp_f32_e32 v77, v77
	v_exp_f32_e32 v78, v78
	v_exp_f32_e32 v79, v79
	v_mfma_f32_32x32x16_bf16 v[18:33], v[244:247], v[196:199], v[18:33]
	v_exp_f32_e32 v80, v80
	v_exp_f32_e32 v81, v81
	v_add_f32_e32 v100, v112, v113
	v_add_f32_e32 v101, v66, v67
	v_add_f32_e32 v100, v100, v114
	v_add_f32_e32 v101, v101, v68
	v_mfma_f32_32x32x16_bf16 v[18:33], v[248:251], v[200:203], v[18:33]
	v_add_f32_e32 v100, v100, v115
	v_add_f32_e32 v101, v101, v69
	v_add_f32_e32 v100, v100, v116
	v_add_f32_e32 v101, v101, v70
	v_add_f32_e32 v100, v100, v117
	v_add_f32_e32 v101, v101, v71
	v_mfma_f32_32x32x16_bf16 v[18:33], v[252:255], v[204:207], v[18:33]
	v_add_f32_e32 v100, v100, v118
	v_add_f32_e32 v101, v101, v72
	v_add_f32_e32 v100, v100, v119
	v_add_f32_e32 v101, v101, v73
	v_add_f32_e32 v100, v100, v120
	v_add_f32_e32 v101, v101, v74
	ds_read_b64_tr_b16 v[192:193], v184 offset:0x600
	ds_read_b64_tr_b16 v[194:195], v184 offset:0xe00
	ds_read_b64_tr_b16 v[196:197], v184 offset:0x1600
	ds_read_b64_tr_b16 v[198:199], v184 offset:0x1e00
	ds_read_b64_tr_b16 v[200:201], v184 offset:0x2600
	ds_read_b64_tr_b16 v[202:203], v184 offset:0x2e00
	ds_read_b64_tr_b16 v[204:205], v184 offset:0x3600
	ds_read_b64_tr_b16 v[206:207], v184 offset:0x3e00
	s_waitcnt lgkmcnt(8)
	v_mfma_f32_32x32x16_bf16 v[34:49], v[238:241], v[82:85], v[34:49]
	v_add_f32_e32 v100, v100, v121
	v_add_f32_e32 v101, v101, v75
	v_add_f32_e32 v100, v100, v122
	v_add_f32_e32 v101, v101, v76
	v_add_f32_e32 v100, v100, v123
	v_add_f32_e32 v101, v101, v77
	v_mfma_f32_32x32x16_bf16 v[34:49], v[244:247], v[86:89], v[34:49]
	v_add_f32_e32 v100, v100, v124
	v_add_f32_e32 v101, v101, v78
	v_add_f32_e32 v100, v100, v125
	v_add_f32_e32 v101, v101, v79
	v_add_f32_e32 v100, v100, v126
	v_add_f32_e32 v101, v101, v80
	v_mfma_f32_32x32x16_bf16 v[34:49], v[248:251], v[90:93], v[34:49]
	v_add_f32_e32 v100, v100, v127
	v_add_f32_e32 v101, v101, v81
	v_add_f32_e32 v100, v100, v101
	v_mov_b32_e32 v102, v100
	v_cvt_pk_bf16_f32 v222, v112, v113
	v_cvt_pk_bf16_f32 v223, v114, v115
	v_mfma_f32_32x32x16_bf16 v[34:49], v[252:255], v[176:179], v[34:49]
	v_cvt_pk_bf16_f32 v224, v116, v117
	v_cvt_pk_bf16_f32 v225, v118, v119
	v_cvt_pk_bf16_f32 v226, v120, v121
	v_cvt_pk_bf16_f32 v227, v122, v123
	v_cvt_pk_bf16_f32 v228, v124, v125
	s_waitcnt lgkmcnt(0)
	v_mfma_f32_32x32x16_bf16 v[50:65], v[238:241], v[192:195], v[50:65]
	v_cvt_pk_bf16_f32 v229, v126, v127
	v_cvt_pk_bf16_f32 v230, v66, v67
	v_cvt_pk_bf16_f32 v231, v68, v69
	v_cvt_pk_bf16_f32 v232, v70, v71
	v_cvt_pk_bf16_f32 v233, v72, v73
	v_mfma_f32_32x32x16_bf16 v[50:65], v[244:247], v[196:199], v[50:65]
	v_cvt_pk_bf16_f32 v234, v74, v75
	v_cvt_pk_bf16_f32 v235, v76, v77
	v_cvt_pk_bf16_f32 v236, v78, v79
	v_cvt_pk_bf16_f32 v237, v80, v81
	v_permlane32_swap_b32_e32 v100, v102
	v_mfma_f32_32x32x16_bf16 v[50:65], v[248:251], v[200:203], v[50:65]
	v_add_f32_e32 v100, v100, v102
	v_add_f32_e32 v149, v149, v100
	v_permlane32_swap_b32_e32 v222, v224
	v_permlane32_swap_b32_e32 v223, v225
	v_permlane32_swap_b32_e32 v226, v228
	v_mfma_f32_32x32x16_bf16 v[50:65], v[252:255], v[204:207], v[50:65]
	v_permlane32_swap_b32_e32 v227, v229
	v_permlane32_swap_b32_e32 v230, v232
	v_permlane32_swap_b32_e32 v231, v233
	v_permlane32_swap_b32_e32 v234, v236
	v_permlane32_swap_b32_e32 v235, v237
	s_waitcnt vmcnt(0)
	s_add_u32 s4, s4, 0x180000
	s_addc_u32 s5, s5, 0
	s_add_i32 s16, s16, 2
	s_and_b64 vcc, exec, s[0:1]
	s_waitcnt vmcnt(0)
	s_barrier
	s_cbranch_vccnz .Ldif_l0_tail

.LBB0_909:
	v_lshl_add_u64 v[178:179], s[4:5], 0, v[172:173]
	s_mov_b32 m0, s30
	v_lshl_add_u64 v[96:97], v[178:179], 0, s[8:9]
	v_lshl_add_u64 v[176:177], s[4:5], 0, v[174:175]
	global_load_lds_dwordx4 v[96:97], off
	v_lshl_add_u64 v[96:97], v[176:177], 0, s[8:9]
	s_mov_b32 m0, s33
	s_nop 0
	global_load_lds_dwordx4 v[96:97], off
	ds_read_b128 v[96:99], v188 offset:32768
	ds_read_b128 v[100:103], v188 offset:36864
	ds_read_b128 v[192:195], v189 offset:32768
	ds_read_b128 v[196:199], v189 offset:36864
	ds_read_b128 v[200:203], v190 offset:32768
	ds_read_b128 v[204:207], v190 offset:36864
	ds_read_b128 v[208:211], v191 offset:32768
	ds_read_b128 v[212:215], v191 offset:36864
	s_waitcnt lgkmcnt(0)
	v_mfma_f32_32x32x16_bf16 v[112:127], v[96:99], v[128:131], 0
	v_mfma_f32_32x32x16_bf16 v[96:111], v[100:103], v[128:131], 0
	v_mfma_f32_32x32x16_bf16 v[112:127], v[192:195], v[132:135], v[112:127]
	v_mfma_f32_32x32x16_bf16 v[96:111], v[196:199], v[132:135], v[96:111]
	v_mfma_f32_32x32x16_bf16 v[112:127], v[200:203], v[136:139], v[112:127]
	v_mfma_f32_32x32x16_bf16 v[96:111], v[204:207], v[136:139], v[96:111]
	v_mfma_f32_32x32x16_bf16 v[112:127], v[208:211], v[140:143], v[112:127]
	v_mfma_f32_32x32x16_bf16 v[96:111], v[212:215], v[140:143], v[96:111]
	ds_read_b64_tr_b16 v[192:193], v185 offset:0
	ds_read_b64_tr_b16 v[194:195], v185 offset:0x800
	ds_read_b64_tr_b16 v[196:197], v185 offset:0x1000
	ds_read_b64_tr_b16 v[198:199], v185 offset:0x1800
	ds_read_b64_tr_b16 v[200:201], v185 offset:0x2000
	ds_read_b64_tr_b16 v[202:203], v185 offset:0x2800
	ds_read_b64_tr_b16 v[204:205], v185 offset:0x3000
	ds_read_b64_tr_b16 v[206:207], v185 offset:0x3800
	ds_read_b64_tr_b16 v[84:85], v185 offset:0x200
	ds_read_b64_tr_b16 v[86:87], v185 offset:0xa00
	ds_read_b64_tr_b16 v[88:89], v185 offset:0x1200
	ds_read_b64_tr_b16 v[90:91], v185 offset:0x1a00
	ds_read_b64_tr_b16 v[208:209], v185 offset:0x2200
	ds_read_b64_tr_b16 v[210:211], v185 offset:0x2a00
	ds_read_b64_tr_b16 v[212:213], v185 offset:0x3200
	ds_read_b64_tr_b16 v[214:215], v185 offset:0x3a00
	s_waitcnt lgkmcnt(8)
	v_mfma_f32_32x32x16_bf16 v[2:17], v[222:225], v[192:195], v[2:17]
	v_exp_f32_e32 v112, v112
	v_exp_f32_e32 v113, v113
	v_exp_f32_e32 v114, v114
	v_exp_f32_e32 v115, v115
	v_exp_f32_e32 v116, v116
	v_exp_f32_e32 v117, v117
	v_mfma_f32_32x32x16_bf16 v[2:17], v[226:229], v[196:199], v[2:17]
	v_exp_f32_e32 v118, v118
	v_exp_f32_e32 v119, v119
	v_exp_f32_e32 v120, v120
	v_exp_f32_e32 v121, v121
	v_exp_f32_e32 v122, v122
	v_exp_f32_e32 v123, v123
	v_mfma_f32_32x32x16_bf16 v[2:17], v[230:233], v[200:203], v[2:17]
	v_exp_f32_e32 v124, v124
	v_exp_f32_e32 v125, v125
	v_exp_f32_e32 v126, v126
	v_exp_f32_e32 v127, v127
	v_exp_f32_e32 v96, v96
	v_exp_f32_e32 v97, v97
	v_mfma_f32_32x32x16_bf16 v[2:17], v[234:237], v[204:207], v[2:17]
	v_exp_f32_e32 v98, v98
	v_exp_f32_e32 v99, v99
	v_exp_f32_e32 v100, v100
	v_exp_f32_e32 v101, v101
	v_exp_f32_e32 v102, v102
	v_exp_f32_e32 v103, v103
	ds_read_b64_tr_b16 v[192:193], v185 offset:0x400
	ds_read_b64_tr_b16 v[194:195], v185 offset:0xc00
	ds_read_b64_tr_b16 v[196:197], v185 offset:0x1400
	ds_read_b64_tr_b16 v[198:199], v185 offset:0x1c00
	ds_read_b64_tr_b16 v[200:201], v185 offset:0x2400
	ds_read_b64_tr_b16 v[202:203], v185 offset:0x2c00
	ds_read_b64_tr_b16 v[204:205], v185 offset:0x3400
	ds_read_b64_tr_b16 v[206:207], v185 offset:0x3c00
	s_waitcnt lgkmcnt(8)
	v_mfma_f32_32x32x16_bf16 v[18:33], v[222:225], v[84:87], v[18:33]
	v_exp_f32_e32 v104, v104
	v_exp_f32_e32 v105, v105
	v_exp_f32_e32 v106, v106
	v_exp_f32_e32 v107, v107
	v_exp_f32_e32 v108, v108
	v_exp_f32_e32 v109, v109
	v_mfma_f32_32x32x16_bf16 v[18:33], v[226:229], v[88:91], v[18:33]
	v_exp_f32_e32 v110, v110
	v_exp_f32_e32 v111, v111
	v_add_f32_e32 v92, v112, v113
	v_add_f32_e32 v93, v96, v97
	v_add_f32_e32 v92, v92, v114
	v_add_f32_e32 v93, v93, v98
	v_mfma_f32_32x32x16_bf16 v[18:33], v[230:233], v[208:211], v[18:33]
	v_add_f32_e32 v92, v92, v115
	v_add_f32_e32 v93, v93, v99
	v_add_f32_e32 v92, v92, v116
	v_add_f32_e32 v93, v93, v100
	v_add_f32_e32 v92, v92, v117
	v_add_f32_e32 v93, v93, v101
	v_mfma_f32_32x32x16_bf16 v[18:33], v[234:237], v[212:215], v[18:33]
	v_add_f32_e32 v92, v92, v118
	v_add_f32_e32 v93, v93, v102
	v_add_f32_e32 v92, v92, v119
	v_add_f32_e32 v93, v93, v103
	v_add_f32_e32 v92, v92, v120
	v_add_f32_e32 v93, v93, v104
	ds_read_b64_tr_b16 v[84:85], v185 offset:0x600
	ds_read_b64_tr_b16 v[86:87], v185 offset:0xe00
	ds_read_b64_tr_b16 v[88:89], v185 offset:0x1600
	ds_read_b64_tr_b16 v[90:91], v185 offset:0x1e00
	ds_read_b64_tr_b16 v[208:209], v185 offset:0x2600
	ds_read_b64_tr_b16 v[210:211], v185 offset:0x2e00
	ds_read_b64_tr_b16 v[212:213], v185 offset:0x3600
	ds_read_b64_tr_b16 v[214:215], v185 offset:0x3e00
	s_waitcnt lgkmcnt(8)
	v_mfma_f32_32x32x16_bf16 v[34:49], v[222:225], v[192:195], v[34:49]
	v_add_f32_e32 v92, v92, v121
	v_add_f32_e32 v93, v93, v105
	v_add_f32_e32 v92, v92, v122
	v_add_f32_e32 v93, v93, v106
	v_add_f32_e32 v92, v92, v123
	v_add_f32_e32 v93, v93, v107
	v_mfma_f32_32x32x16_bf16 v[34:49], v[226:229], v[196:199], v[34:49]
	v_add_f32_e32 v92, v92, v124
	v_add_f32_e32 v93, v93, v108
	v_add_f32_e32 v92, v92, v125
	v_add_f32_e32 v93, v93, v109
	v_add_f32_e32 v92, v92, v126
	v_add_f32_e32 v93, v93, v110
	v_mfma_f32_32x32x16_bf16 v[34:49], v[230:233], v[200:203], v[34:49]
	v_add_f32_e32 v92, v92, v127
	v_add_f32_e32 v93, v93, v111
	v_add_f32_e32 v92, v92, v93
	v_mov_b32_e32 v94, v92
	v_cvt_pk_bf16_f32 v238, v112, v113
	v_cvt_pk_bf16_f32 v239, v114, v115
	v_mfma_f32_32x32x16_bf16 v[34:49], v[234:237], v[204:207], v[34:49]
	v_cvt_pk_bf16_f32 v240, v116, v117
	v_cvt_pk_bf16_f32 v241, v118, v119
	v_cvt_pk_bf16_f32 v244, v120, v121
	v_cvt_pk_bf16_f32 v245, v122, v123
	v_cvt_pk_bf16_f32 v246, v124, v125
	s_waitcnt lgkmcnt(0)
	v_mfma_f32_32x32x16_bf16 v[50:65], v[222:225], v[84:87], v[50:65]
	v_cvt_pk_bf16_f32 v247, v126, v127
	v_cvt_pk_bf16_f32 v248, v96, v97
	v_cvt_pk_bf16_f32 v249, v98, v99
	v_cvt_pk_bf16_f32 v250, v100, v101
	v_cvt_pk_bf16_f32 v251, v102, v103
	v_mfma_f32_32x32x16_bf16 v[50:65], v[226:229], v[88:91], v[50:65]
	v_cvt_pk_bf16_f32 v252, v104, v105
	v_cvt_pk_bf16_f32 v253, v106, v107
	v_cvt_pk_bf16_f32 v254, v108, v109
	v_cvt_pk_bf16_f32 v255, v110, v111
	v_permlane32_swap_b32_e32 v92, v94
	v_mfma_f32_32x32x16_bf16 v[50:65], v[230:233], v[208:211], v[50:65]
	v_add_f32_e32 v92, v92, v94
	v_add_f32_e32 v149, v149, v92
	v_permlane32_swap_b32_e32 v238, v240
	v_permlane32_swap_b32_e32 v239, v241
	v_permlane32_swap_b32_e32 v244, v246
	v_mfma_f32_32x32x16_bf16 v[50:65], v[234:237], v[212:215], v[50:65]
	v_permlane32_swap_b32_e32 v245, v247
	v_permlane32_swap_b32_e32 v248, v250
	v_permlane32_swap_b32_e32 v249, v251
	v_permlane32_swap_b32_e32 v252, v254
	v_permlane32_swap_b32_e32 v253, v255
	s_waitcnt vmcnt(0)
	s_cmp_ge_u32 s16, s11
	s_cselect_b64 s[0:1], -1, 0
	s_and_b64 vcc, exec, s[0:1]
	s_waitcnt vmcnt(0)
	s_barrier
	s_cbranch_vccnz .LBB0_906
	s_mov_b64 s[18:19], 0x15c81800
	v_lshl_add_u64 v[66:67], v[180:181], 0, s[18:19]
	s_mov_b32 m0, s31
	s_nop 0
	global_load_lds_dwordx4 v[66:67], off
	s_branch .LBB0_906
.Ldif_l0_tail:
	s_lshl_b32 s0, s10, 2
	s_add_i32 s4, s0, 0
	s_add_i32 s4, s4, 0x1e000
	v_readlane_b32 s44, v243, 63
	v_readlane_b32 s45, v242, 0
	v_readlane_b32 s46, v242, 1
	v_readlane_b32 s47, v242, 2
	v_readlane_b32 s48, v242, 3
	v_readlane_b32 s49, v242, 4
	v_readlane_b32 s50, v242, 5
	v_readlane_b32 s51, v242, 6
	v_readlane_b32 s52, v242, 7
	v_readlane_b32 s53, v242, 8
	v_readlane_b32 s54, v242, 9
	v_readlane_b32 s55, v242, 10
	v_readlane_b32 s56, v242, 11
	v_readlane_b32 s57, v242, 12
	v_readlane_b32 s58, v242, 13
	v_readlane_b32 s59, v242, 14
	ds_read_b64_tr_b16 v[192:193], v185 offset:0
	ds_read_b64_tr_b16 v[194:195], v185 offset:0x800
	ds_read_b64_tr_b16 v[196:197], v185 offset:0x1000
	ds_read_b64_tr_b16 v[198:199], v185 offset:0x1800
	ds_read_b64_tr_b16 v[200:201], v185 offset:0x2000
	ds_read_b64_tr_b16 v[202:203], v185 offset:0x2800
	ds_read_b64_tr_b16 v[204:205], v185 offset:0x3000
	ds_read_b64_tr_b16 v[206:207], v185 offset:0x3800
	ds_read_b64_tr_b16 v[84:85], v185 offset:0x200
	ds_read_b64_tr_b16 v[86:87], v185 offset:0xa00
	ds_read_b64_tr_b16 v[88:89], v185 offset:0x1200
	ds_read_b64_tr_b16 v[90:91], v185 offset:0x1a00
	ds_read_b64_tr_b16 v[208:209], v185 offset:0x2200
	ds_read_b64_tr_b16 v[210:211], v185 offset:0x2a00
	ds_read_b64_tr_b16 v[212:213], v185 offset:0x3200
	ds_read_b64_tr_b16 v[214:215], v185 offset:0x3a00
	s_waitcnt lgkmcnt(8)
	v_mfma_f32_32x32x16_bf16 v[2:17], v[222:225], v[192:195], v[2:17]
	v_mfma_f32_32x32x16_bf16 v[2:17], v[226:229], v[196:199], v[2:17]
	v_mfma_f32_32x32x16_bf16 v[2:17], v[230:233], v[200:203], v[2:17]
	v_mfma_f32_32x32x16_bf16 v[2:17], v[234:237], v[204:207], v[2:17]
	ds_read_b64_tr_b16 v[192:193], v185 offset:0x400
	ds_read_b64_tr_b16 v[194:195], v185 offset:0xc00
	ds_read_b64_tr_b16 v[196:197], v185 offset:0x1400
	ds_read_b64_tr_b16 v[198:199], v185 offset:0x1c00
	ds_read_b64_tr_b16 v[200:201], v185 offset:0x2400
	ds_read_b64_tr_b16 v[202:203], v185 offset:0x2c00
	ds_read_b64_tr_b16 v[204:205], v185 offset:0x3400
	ds_read_b64_tr_b16 v[206:207], v185 offset:0x3c00
	s_waitcnt lgkmcnt(8)
	v_mfma_f32_32x32x16_bf16 v[18:33], v[222:225], v[84:87], v[18:33]
	v_mfma_f32_32x32x16_bf16 v[18:33], v[226:229], v[88:91], v[18:33]
	v_mfma_f32_32x32x16_bf16 v[18:33], v[230:233], v[208:211], v[18:33]
	v_mfma_f32_32x32x16_bf16 v[18:33], v[234:237], v[212:215], v[18:33]
	ds_read_b64_tr_b16 v[84:85], v185 offset:0x600
	ds_read_b64_tr_b16 v[86:87], v185 offset:0xe00
	ds_read_b64_tr_b16 v[88:89], v185 offset:0x1600
	ds_read_b64_tr_b16 v[90:91], v185 offset:0x1e00
	ds_read_b64_tr_b16 v[208:209], v185 offset:0x2600
	ds_read_b64_tr_b16 v[210:211], v185 offset:0x2e00
	ds_read_b64_tr_b16 v[212:213], v185 offset:0x3600
	ds_read_b64_tr_b16 v[214:215], v185 offset:0x3e00
	s_waitcnt lgkmcnt(8)
	v_mfma_f32_32x32x16_bf16 v[34:49], v[222:225], v[192:195], v[34:49]
	v_mfma_f32_32x32x16_bf16 v[34:49], v[226:229], v[196:199], v[34:49]
	v_mfma_f32_32x32x16_bf16 v[34:49], v[230:233], v[200:203], v[34:49]
	v_mfma_f32_32x32x16_bf16 v[34:49], v[234:237], v[204:207], v[34:49]
	s_waitcnt lgkmcnt(0)
	v_mfma_f32_32x32x16_bf16 v[50:65], v[222:225], v[84:87], v[50:65]
	s_barrier
	v_mfma_f32_32x32x16_bf16 v[50:65], v[226:229], v[88:91], v[50:65]
	v_mfma_f32_32x32x16_bf16 v[50:65], v[230:233], v[208:211], v[50:65]
	v_mfma_f32_32x32x16_bf16 v[50:65], v[234:237], v[212:215], v[50:65]
	s_and_saveexec_b64 s[0:1], s[2:3]
	s_cbranch_execz .LBB0_897
	v_lshl_add_u32 v66, v165, 2, s4
	ds_write_b32 v66, v149
	s_branch .LBB0_897
